# P7 chunk-out: operand prefetch 3 items deep (4 rotating register sets, exact counted vmcnt per item: 12 per younger prefetch + 8 per younger store group, max 60 outstanding); on top of all20
# baseline (speedup 1.0000x reference)
; #define GAS __attribute__((address_space(1)))
; #define LAS __attribute__((address_space(3)))
; __device__ __forceinline__ void chunk_out_load(Frame& F, int item, ChunkOutOps& o, int w, int fr, int fq) {
;     const bf16* S = (const bf16*)(F.ws + WS_S) + (size_t)item * 4096; const bf16* RP = (const bf16*)(F.ws + WS_RP) + (size_t)item * 4096; const bf16* Y0 = (const bf16*)(F.ws + WS_Y0) + (size_t)item * 4096;
; #pragma unroll
;     for (int q = 0; q < 2; ++q) { const int tw = 2 * w + q, p0 = 16 * (tw >> 2), q0 = 16 * (tw & 3);
;         o.y0[q] = *(const GAS v2u*)(Y0 + (p0 + fr) * 64 + q0 + 4 * fq);
; #pragma unroll
;         for (int k = 0; k < 2; ++k) { o.sf[q][k] = *(const GAS bf16x8*)(S + (q0 + fr) * 64 + k * 32 + fq * 8); o.rf[q][k] = *(const GAS bf16x8*)(RP + (p0 + fr) * 64 + k * 32 + fq * 8); } }
; }
; __device__ __forceinline__ void rwkv_chunk_out_all(Frame& F) {
;     const float* PRM = (const float*)(F.ws + WS_PRM);
;     LAS unsigned char* L = F.lds;
;     const int lane = F.lane, w = F.wave, fr = lane & 15, fq = lane >> 4;
;     ChunkOutOps cur, nxt;
;     int item = F.vcu;
;     if (item < NITEM) chunk_out_load(F, item, cur, w, fr, fq);
.LBB0_1673:
	s_load_dwordx2 s[2:3], s[72:73], 0x108
	s_waitcnt lgkmcnt(0)
	s_cmp_lt_i32 s2, 8
	s_cselect_b64 s[0:1], -1, 0
	s_cmp_gt_i32 s3, 7
	s_cselect_b64 s[2:3], -1, 0
	s_and_b64 s[0:1], s[0:1], s[2:3]
	s_andn2_b64 vcc, exec, s[0:1]
	s_cbranch_vccnz .LBB0_1716
	v_readlane_b32 s0, v254, 2
	s_cmpk_gt_i32 s0, 0x7ff
	v_readlane_b32 s1, v254, 3
	s_cbranch_scc1 .LBB0_1679
	s_add_u32 s6, s86, 0x200000
	s_addc_u32 s7, s87, 0
	s_add_u32 s10, s86, 0xe000000
	s_addc_u32 s11, s87, 0
	s_add_u32 s12, s86, 0xf000000
	s_addc_u32 s13, s87, 0
	s_lshl_b32 s0, s93, 5
	s_lshl_b32 s18, s93, 3
	s_and_b32 s19, s0, 32
	s_and_b32 s1, s18, 0x1ffffff0
	s_or_b32 s20, s19, 16
	v_and_b32_e32 v4, 15, v208
	s_add_u32 s0, s86, 0x14800
	v_or_b32_e32 v20, s1, v4
	s_addc_u32 s1, s87, 0
	s_add_u32 s2, s86, 0x15000
	s_addc_u32 s3, s87, 0
	s_lshl_b32 s8, s93, 4
	v_readlane_b32 s22, v254, 2
	s_add_u32 s4, s86, 0x7000000
	v_readlane_b32 s23, v254, 3
	s_addc_u32 s5, s87, 0
	s_ashr_i32 s23, s22, 31
	s_lshl_b64 s[14:15], s[22:23], 13
	v_or_b32_e32 v21, s19, v4
	v_or_b32_e32 v22, s20, v4
	v_lshlrev_b32_e32 v4, 6, v208
	s_add_u32 s16, s6, s14
	v_mov_b32_e32 v57, 0
	v_ashrrev_i32_e32 v5, 31, v4
	v_lshlrev_b32_e32 v56, 7, v20
	s_addc_u32 s17, s7, s15
	v_ashrrev_i32_e32 v2, 4, v208
	s_mov_b32 s9, 0
	v_lshl_add_u64 v[4:5], v[4:5], 1, s[86:87]
	v_lshl_add_u64 v[6:7], s[12:13], 0, v[56:57]
	s_add_u32 s12, s12, s14
	v_lshlrev_b32_e32 v0, 2, v2
	v_lshlrev_b32_e32 v2, 3, v2
	v_lshl_add_u64 v[4:5], v[4:5], 0, s[8:9]
	s_addc_u32 s13, s13, s15
	s_lshl_b32 s8, s19, 1
	v_ashrrev_i32_e32 v3, 31, v2
	v_lshl_add_u64 v[10:11], s[10:11], 0, v[56:57]
	s_add_u32 s10, s10, s14
	v_ashrrev_i32_e32 v1, 31, v0
	v_lshlrev_b64 v[2:3], 1, v[2:3]
	s_addc_u32 s11, s11, s15
	v_lshlrev_b64 v[8:9], 1, v[0:1]
	v_lshl_add_u64 v[12:13], s[16:17], 0, v[2:3]
	v_lshlrev_b32_e32 v14, 7, v22
	v_mov_b32_e32 v15, v57
	v_lshl_add_u64 v[16:17], s[12:13], 0, v[56:57]
	v_lshl_add_u64 v[18:19], s[10:11], 0, v[56:57]
	v_lshlrev_b32_e32 v56, 7, v21
	v_lshl_add_u64 v[14:15], v[12:13], 0, v[14:15]
	v_lshl_add_u64 v[16:17], v[16:17], 0, v[8:9]
	v_lshl_add_u64 v[12:13], v[12:13], 0, v[56:57]
	v_lshl_add_u64 v[16:17], v[16:17], 0, s[8:9]
	v_lshl_add_u64 v[18:19], v[18:19], 0, v[2:3]


; #define GAS __attribute__((address_space(1)))
; __device__ __forceinline__ void rwkv_chunk_out_all(Frame& F) {
;     ...
;     if (item < NITEM) chunk_out_load(F, item, cur, w, fr, fq);
;     for (; item < NITEM; item += F.G) {
;         const int bh = item / NCH, c = item % NCH, b = bh / RW_H, h = bh % RW_H; const int row0 = b * T + c * CH;
;         const int ch = lane, gc = h * 64 + ch;
;         const bf16* VB = (const bf16*)(F.ws + WS_VB) + (size_t)item * 4096; const bf16* G = (const bf16*)(F.ws + WS_G) + (size_t)item * 4096;
;         const v4u vbq = *(const GAS v4u*)(VB + ch * 64 + 8 * w), ggq = *(const GAS v4u*)(G + ch * 64 + 8 * w);
;         const int inext = item + F.G;
;         if (inext < NITEM) chunk_out_load(F, inext, nxt, w, fr, fq);
;     ...
;             const float gw = (PRM + 4608)[gc], gb = (PRM + 5120)[gc];
;             bf16* YM = (bf16*)(F.ws + WS_YMIX);
	s_movk_i32 s10, 0x41
	v_mad_u64_u32 v[0:1], s[10:11], v20, s10, v[0:1]
	v_lshl_add_u64 v[62:63], s[6:7], 0, v[2:3]
	s_lshl_b32 s6, s22, 6
	s_mul_i32 s10, s93, 0x208
	s_add_i32 s6, s6, s18
	v_add_lshl_u32 v78, v208, s10, 2
	s_mov_b64 s[10:11], 0xc000000
	s_or_b32 s12, s6, 7
	s_mov_b32 s6, s22
	v_lshlrev_b32_e32 v12, 6, v21
	v_lshlrev_b32_e32 v14, 6, v22
	v_add_lshl_u32 v13, v0, s19, 2
	v_add_lshl_u32 v15, s20, v0, 2
	v_add_u32_e32 v16, 0x104, v78
	v_add_u32_e32 v17, 0x208, v78
	v_add_u32_e32 v18, 0x30c, v78
	v_add_u32_e32 v19, 0x410, v78
	v_add_u32_e32 v20, 0x514, v78
	v_add_u32_e32 v21, 0x618, v78
	v_add_u32_e32 v22, 0x71c, v78
	v_lshl_add_u64 v[58:59], v[4:5], 0, s[10:11]
	s_mov_b64 s[10:11], 0xd000000
	v_lshl_add_u64 v[0:1], v[6:7], 0, v[8:9]
	v_writelane_b32 v254, s6, 2
	v_lshl_add_u64 v[60:61], v[4:5], 0, s[10:11]
	v_lshl_add_u64 v[64:65], v[10:11], 0, v[2:3]
	v_lshl_add_u64 v[66:67], v[0:1], 0, s[8:9]
	s_lshl_b32 s13, s77, 6
	v_lshlrev_b32_e32 v56, 1, v12
	v_lshlrev_b32_e32 v68, 1, v14
	v_add_u32_e32 v79, 0, v13
	v_add_u32_e32 v80, 0, v15
	v_add_u32_e32 v81, 0, v16
	v_add_u32_e32 v82, 0, v17
	v_add_u32_e32 v83, 0, v18
	v_add_u32_e32 v84, 0, v19
	v_add_u32_e32 v85, 0, v20
	v_add_u32_e32 v86, 0, v21
	v_add_u32_e32 v87, 0, v22
	v_mov_b32_e32 v88, 0x3a27c5ac
	v_mov_b32_e32 v89, 0xbc800000
	v_mov_b32_e32 v90, 0x3c800000
	v_writelane_b32 v254, s7, 3
	s_mov_b32 s10, s22
	v_mov_b32_e32 v69, v57
	s_mov_b32 s25, s10
	s_mov_b32 s28, s25
	s_ashr_i32 s29, s28, 31
	s_lshl_b64 s[30:31], s[28:29], 13
	v_lshl_add_u64 v[2:3], v[62:63], 0, s[30:31]
	v_lshl_add_u64 v[4:5], v[2:3], 0, v[56:57]
	global_load_dwordx4 v[102:105], v[4:5], off
	global_load_dwordx4 v[106:109], v[4:5], off offset:64
	v_lshl_add_u64 v[4:5], v[64:65], 0, s[30:31]
	global_load_dwordx4 v[110:113], v[4:5], off
	global_load_dwordx4 v[114:117], v[4:5], off offset:64
	v_lshl_add_u64 v[4:5], v[66:67], 0, s[30:31]
	global_load_dwordx2 v[126:127], v[4:5], off
	global_load_dwordx2 v[128:129], v[4:5], off offset:32
	v_lshl_add_u64 v[4:5], v[2:3], 0, v[68:69]
	global_load_dwordx4 v[118:121], v[4:5], off
	global_load_dwordx4 v[122:125], v[4:5], off offset:64
	v_lshl_add_u64 v[4:5], v[58:59], 0, s[30:31]
	global_load_dwordx4 v[130:133], v[4:5], off
	v_lshl_add_u64 v[4:5], v[60:61], 0, s[30:31]
	global_load_dwordx4 v[134:137], v[4:5], off
	s_lshr_b32 s99, s28, 6
	s_and_b32 s99, s99, 7
	s_lshl_b32 s99, s99, 6
	v_add_lshl_u32 v6, v208, s99, 2
	v_mov_b32_e32 v7, 0
	v_lshl_add_u64 v[4:5], s[0:1], 0, v[6:7]
	global_load_dword v138, v[4:5], off
	v_lshl_add_u64 v[4:5], s[2:3], 0, v[6:7]
	global_load_dword v139, v[4:5], off
	s_add_i32 s28, s25, s77
	s_cmpk_gt_i32 s28, 0x7ff
	s_cbranch_scc1 .Lp7d_pre_done
	s_ashr_i32 s29, s28, 31
	s_lshl_b64 s[30:31], s[28:29], 13
	v_lshl_add_u64 v[2:3], v[62:63], 0, s[30:31]
	v_lshl_add_u64 v[4:5], v[2:3], 0, v[56:57]
	global_load_dwordx4 v[140:143], v[4:5], off
	global_load_dwordx4 v[144:147], v[4:5], off offset:64
	v_lshl_add_u64 v[4:5], v[64:65], 0, s[30:31]
	global_load_dwordx4 v[148:151], v[4:5], off
	global_load_dwordx4 v[152:155], v[4:5], off offset:64
	v_lshl_add_u64 v[4:5], v[66:67], 0, s[30:31]
	global_load_dwordx2 v[164:165], v[4:5], off
	global_load_dwordx2 v[166:167], v[4:5], off offset:32
	v_lshl_add_u64 v[4:5], v[2:3], 0, v[68:69]
	global_load_dwordx4 v[156:159], v[4:5], off
	global_load_dwordx4 v[160:163], v[4:5], off offset:64
	v_lshl_add_u64 v[4:5], v[58:59], 0, s[30:31]
	global_load_dwordx4 v[168:171], v[4:5], off
	v_lshl_add_u64 v[4:5], v[60:61], 0, s[30:31]
	global_load_dwordx4 v[172:175], v[4:5], off
	s_lshr_b32 s99, s28, 6
	s_and_b32 s99, s99, 7
	s_lshl_b32 s99, s99, 6
	v_add_lshl_u32 v6, v208, s99, 2
	v_mov_b32_e32 v7, 0
	v_lshl_add_u64 v[4:5], s[0:1], 0, v[6:7]
	global_load_dword v176, v[4:5], off
	v_lshl_add_u64 v[4:5], s[2:3], 0, v[6:7]
	global_load_dword v177, v[4:5], off
	s_add_i32 s28, s28, s77
	s_cmpk_gt_i32 s28, 0x7ff
	s_cbranch_scc1 .Lp7d_pre_done
	s_ashr_i32 s29, s28, 31
	s_lshl_b64 s[30:31], s[28:29], 13
	v_lshl_add_u64 v[2:3], v[62:63], 0, s[30:31]
	v_lshl_add_u64 v[4:5], v[2:3], 0, v[56:57]
	global_load_dwordx4 v[178:181], v[4:5], off
	global_load_dwordx4 v[182:185], v[4:5], off offset:64
	v_lshl_add_u64 v[4:5], v[64:65], 0, s[30:31]
	global_load_dwordx4 v[186:189], v[4:5], off
	global_load_dwordx4 v[190:193], v[4:5], off offset:64
	v_lshl_add_u64 v[4:5], v[66:67], 0, s[30:31]
	global_load_dwordx2 v[202:203], v[4:5], off
	global_load_dwordx2 v[204:205], v[4:5], off offset:32
	v_lshl_add_u64 v[4:5], v[2:3], 0, v[68:69]
	global_load_dwordx4 v[194:197], v[4:5], off
	global_load_dwordx4 v[198:201], v[4:5], off offset:64
	v_lshl_add_u64 v[4:5], v[58:59], 0, s[30:31]
	global_load_dwordx4 v[210:213], v[4:5], off
	v_lshl_add_u64 v[4:5], v[60:61], 0, s[30:31]
	global_load_dwordx4 v[214:217], v[4:5], off
	s_lshr_b32 s99, s28, 6
	s_and_b32 s99, s99, 7
	s_lshl_b32 s99, s99, 6
	v_add_lshl_u32 v6, v208, s99, 2
	v_mov_b32_e32 v7, 0
	v_lshl_add_u64 v[4:5], s[0:1], 0, v[6:7]
	global_load_dword v206, v[4:5], off
	v_lshl_add_u64 v[4:5], s[2:3], 0, v[6:7]
	global_load_dword v207, v[4:5], off
.Lp7d_pre_done:
	s_mov_b32 s24, 0
	s_mov_b32 s27, 0
	s_branch .Lp7d_top


; #define LAS __attribute__((address_space(3)))
; #define LBAR() asm volatile("s_waitcnt lgkmcnt(0)\n\ts_barrier" ::: "memory")
; __device__ __forceinline__ void rwkv_chunk_out_all(Frame& F) {
;     ...
;         for (int q = 0; q < 2; ++q) { const int tw = 2 * w + q, p0 = 16 * (tw >> 2), q0 = 16 * (tw & 3);
;             f32x4 a = (f32x4){bflo(cur.y0[q].x), bfhi(cur.y0[q].x), bflo(cur.y0[q].y), bfhi(cur.y0[q].y)};
; #pragma unroll
;             for (int k = 0; k < 2; ++k) a = __builtin_amdgcn_mfma_f32_16x16x32_bf16(cur.sf[q][k], cur.rf[q][k], a, 0, 0, 0);
; #pragma unroll
;             for (int v = 0; v < 4; ++v) *(LAS float*)(L + L_YL + ((p0 + fr) * 65 + q0 + 4 * fq + v) * 4) = a[v];
;         }
;         LBAR();
.Lp7_body:
	v_lshlrev_b32_e32 v92, 16, v76
	v_and_b32_e32 v93, 0xffff0000, v76
	v_lshlrev_b32_e32 v94, 16, v77
	v_and_b32_e32 v95, 0xffff0000, v77
	s_lshr_b32 s7, s11, 26
	s_add_i32 s7, s10, s7
	v_mfma_f32_16x16x32_bf16 v[52:55], v[52:55], v[36:39], v[92:95]
	s_ashr_i32 s7, s7, 6
	s_lshr_b32 s11, s11, 23
	s_add_i32 s10, s10, s11
	v_mfma_f32_16x16x32_bf16 v[48:51], v[48:51], v[32:35], v[52:55]
	s_lshr_b32 s11, s7, 29
	s_add_i32 s11, s7, s11
	s_and_b32 s11, s11, 0x3fffff8
	s_nop 0
	v_lshlrev_b32_e32 v52, 16, v74
	v_and_b32_e32 v53, 0xffff0000, v74
	v_lshlrev_b32_e32 v54, 16, v75
	v_and_b32_e32 v55, 0xffff0000, v75
	s_sub_i32 s11, s7, s11
	ds_write2_b32 v79, v48, v49 offset1:1
	ds_write2_b32 v79, v50, v51 offset0:2 offset1:3
	v_mfma_f32_16x16x32_bf16 v[36:39], v[44:47], v[36:39], v[52:55]
	v_lshl_add_u32 v44, s11, 6, v208
	v_ashrrev_i32_e32 v45, 31, v44
	s_lshl_b32 s10, s10, 3
	v_mfma_f32_16x16x32_bf16 v[32:35], v[40:43], v[32:35], v[36:39]
	s_nop 7
	ds_write2_b32 v80, v32, v33 offset1:1
	ds_write2_b32 v80, v34, v35 offset0:2 offset1:3
	v_lshlrev_b64 v[32:33], 2, v[44:45]
	s_waitcnt lgkmcnt(0)
	s_barrier
	v_lshl_add_u64 v[34:35], s[0:1], 0, v[32:33]
	v_lshl_add_u64 v[32:33], s[2:3], 0, v[32:33]

; #define LAS __attribute__((address_space(3)))
; __device__ __forceinline__ void rwkv_chunk_out_all(Frame& F) {
;     ...
;         {
;             const float gw = (PRM + 4608)[gc], gb = (PRM + 5120)[gc];
;             bf16* YM = (bf16*)(F.ws + WS_YMIX);
;             float yv[8], sm[8], sv[8];
; #pragma unroll
;             for (int tt = 0; tt < 8; ++tt) { yv[tt] = *(const LAS float*)(L + L_YL + ((8 * w + tt) * 65 + ch) * 4); sm[tt] = yv[tt]; }
;             wave_sum8(sm);
; #pragma unroll
;             for (int tt = 0; tt < 8; ++tt) { yv[tt] -= sm[tt] * (1.f / 64.f); sv[tt] = yv[tt] * yv[tt]; }
;             wave_sum8(sv);
; #pragma unroll
;             for (int tt = 0; tt < 8; ++tt) { const int t = 8 * w + tt;
;                 const float yn = yv[tt] * __builtin_amdgcn_rsqf(sv[tt] * (1.f / 64.f) + GN_EPS) * gw + gb;
	v_mov_b32_e32 v36, v100
	v_mov_b32_e32 v37, v101
	v_add_u32_e32 v32, 0, v78
	ds_read_b32 v34, v32
	ds_read_b32 v38, v81
	ds_read_b32 v39, v82
	ds_read_b32 v40, v84
	ds_read_b32 v41, v83
	ds_read_b32 v42, v85
	ds_read_b32 v43, v86
	ds_read_b32 v46, v87
	s_waitcnt lgkmcnt(4)
	v_mov_b32_e32 v32, v40
	v_mov_b32_e32 v33, v34
	s_nop 1
	v_permlane32_swap_b32_e32 v33, v32
	v_add_f32_e32 v32, v33, v32
	s_waitcnt lgkmcnt(2)
	v_mov_b32_e32 v33, v42
	v_mov_b32_e32 v35, v38
	s_nop 1
	v_permlane32_swap_b32_e32 v35, v33
	v_add_f32_e32 v33, v35, v33
	v_mov_b32_e32 v35, v39
	s_waitcnt lgkmcnt(1)
	v_mov_b32_e32 v47, v43
	s_nop 1
	v_permlane32_swap_b32_e32 v35, v47
	v_add_f32_e32 v35, v35, v47
	s_nop 1
	v_permlane16_swap_b32_e32 v32, v35
	v_add_f32_e32 v32, v32, v35
	v_mov_b32_e32 v47, v41
	s_waitcnt lgkmcnt(0)
	v_mov_b32_e32 v48, v46
	v_add_f32_dpp v32, v32, v32 quad_perm:[1,0,3,2] row_mask:0xf bank_mask:0xf bound_ctrl:1
	s_nop 0
	v_permlane32_swap_b32_e32 v47, v48
	v_add_f32_dpp v32, v32, v32 quad_perm:[2,3,0,1] row_mask:0xf bank_mask:0xf bound_ctrl:1
	v_add_f32_e32 v47, v47, v48
	s_nop 1
	v_permlane16_swap_b32_e32 v33, v47
	v_add_f32_dpp v32, v32, v32 row_half_mirror row_mask:0xf bank_mask:0xf bound_ctrl:1
	v_add_f32_e32 v33, v33, v47
	s_and_b32 s10, s10, 0xfffff000
	v_add_f32_dpp v32, v32, v32 row_mirror row_mask:0xf bank_mask:0xf bound_ctrl:1
	v_add_f32_dpp v33, v33, v33 quad_perm:[1,0,3,2] row_mask:0xf bank_mask:0xf bound_ctrl:1
	v_readlane_b32 s11, v32, 0
	v_readlane_b32 s14, v32, 16
	v_readlane_b32 s15, v32, 32
	v_readlane_b32 s16, v32, 48
	v_fmac_f32_e32 v34, s11, v89
	v_fmac_f32_e32 v39, s14, v89
	v_fmac_f32_e32 v40, s15, v89
	v_fmac_f32_e32 v43, s16, v89
	v_mul_f32_e32 v32, v34, v34
	v_mul_f32_e32 v35, v39, v39
	v_mul_f32_e32 v48, v40, v40
	v_mul_f32_e32 v50, v43, v43
	s_nop 0
	v_permlane32_swap_b32_e32 v32, v48
	v_permlane32_swap_b32_e32 v35, v50
	v_add_f32_e32 v32, v32, v48
	v_add_f32_e32 v35, v35, v50
	s_nop 1
	v_permlane16_swap_b32_e32 v32, v35
	v_add_f32_dpp v33, v33, v33 quad_perm:[2,3,0,1] row_mask:0xf bank_mask:0xf bound_ctrl:1
	v_add_f32_e32 v32, v32, v35
	s_lshl_b32 s7, s7, 12
	v_add_f32_dpp v33, v33, v33 row_half_mirror row_mask:0xf bank_mask:0xf bound_ctrl:1
	v_add_f32_dpp v32, v32, v32 quad_perm:[1,0,3,2] row_mask:0xf bank_mask:0xf bound_ctrl:1
	s_sub_i32 s7, s10, s7
	v_add_f32_dpp v33, v33, v33 row_mirror row_mask:0xf bank_mask:0xf bound_ctrl:1
	v_add_f32_dpp v32, v32, v32 quad_perm:[2,3,0,1] row_mask:0xf bank_mask:0xf bound_ctrl:1
	v_readlane_b32 s17, v33, 0
	v_readlane_b32 s18, v33, 16
	v_readlane_b32 s19, v33, 32
	v_readlane_b32 s20, v33, 48
	v_add_f32_dpp v32, v32, v32 row_half_mirror row_mask:0xf bank_mask:0xf bound_ctrl:1
	v_fmac_f32_e32 v38, s17, v89
	v_fmac_f32_e32 v41, s18, v89
	v_fmac_f32_e32 v42, s19, v89
	v_fmac_f32_e32 v46, s20, v89
	v_add_f32_dpp v32, v32, v32 row_mirror row_mask:0xf bank_mask:0xf bound_ctrl:1
	v_mul_f32_e32 v33, v38, v38
	v_mul_f32_e32 v47, v41, v41
	v_mul_f32_e32 v49, v42, v42
	v_mul_f32_e32 v51, v46, v46
	v_readlane_b32 s11, v32, 0
	v_permlane32_swap_b32_e32 v33, v49
	v_permlane32_swap_b32_e32 v47, v51
	v_readlane_b32 s16, v32, 16
	v_readlane_b32 s17, v32, 32
	v_readlane_b32 s18, v32, 48
	v_fma_f32 v32, s11, v90, v88
	v_add_f32_e32 v33, v33, v49
	v_add_f32_e32 v47, v47, v51
	v_rsq_f32_e32 v35, v32
	s_nop 0
	v_permlane16_swap_b32_e32 v33, v47
	v_add_f32_e32 v33, v33, v47
	v_mul_f32_e32 v34, v34, v35
	v_fma_f32 v34, v36, v34, v37
	v_add_f32_dpp v33, v33, v33 quad_perm:[1,0,3,2] row_mask:0xf bank_mask:0xf bound_ctrl:1
	v_lshlrev_b32_e32 v35, 16, v28
	v_add_f32_e32 v34, v34, v35
	v_add_f32_dpp v33, v33, v33 quad_perm:[2,3,0,1] row_mask:0xf bank_mask:0xf bound_ctrl:1
	v_lshlrev_b32_e32 v35, 16, v24
	v_mul_f32_e32 v34, v34, v35
	v_add_f32_dpp v33, v33, v33 row_half_mirror row_mask:0xf bank_mask:0xf bound_ctrl:1
	s_add_i32 s10, s12, s7
	s_add_i32 s14, s10, -7
	v_add_f32_dpp v33, v33, v33 row_mirror row_mask:0xf bank_mask:0xf bound_ctrl:1
	s_ashr_i32 s15, s14, 31
	v_readlane_b32 s19, v33, 0
	v_readlane_b32 s20, v33, 16
	v_readlane_b32 s21, v33, 32
	v_readlane_b32 s22, v33, 48
	v_lshl_add_u64 v[32:33], v[44:45], 1, s[4:5]
	v_cvt_pk_bf16_f32 v44, v34, s0
	v_fma_f32 v34, s19, v90, v88
	v_rsq_f32_e32 v45, v34
	s_lshl_b64 s[14:15], s[14:15], 11
	v_lshl_add_u64 v[34:35], v[32:33], 0, s[14:15]
	s_waitcnt vmcnt(52)
; #define GAS __attribute__((address_space(1)))
; __device__ __forceinline__ unsigned f2bf(float f) { return pk2(f, 0.f) & 0xffffu; }
; #define LBAR() asm volatile("s_waitcnt lgkmcnt(0)\n\ts_barrier" ::: "memory")
; __device__ __forceinline__ void rwkv_chunk_out_all(Frame& F) {
;     ...
;     for (; item < NITEM; item += F.G) {
;         const int bh = item / NCH, c = item % NCH, b = bh / RW_H, h = bh % RW_H; const int row0 = b * T + c * CH;
;         const int ch = lane, gc = h * 64 + ch;
;         const bf16* VB = (const bf16*)(F.ws + WS_VB) + (size_t)item * 4096; const bf16* G = (const bf16*)(F.ws + WS_G) + (size_t)item * 4096;
;         const v4u vbq = *(const GAS v4u*)(VB + ch * 64 + 8 * w), ggq = *(const GAS v4u*)(G + ch * 64 + 8 * w);
;         const int inext = item + F.G;
;         if (inext < NITEM) chunk_out_load(F, inext, nxt, w, fr, fq);
;     ...
;             for (int tt = 0; tt < 8; ++tt) { const int t = 8 * w + tt;
;                 const float yn = yv[tt] * __builtin_amdgcn_rsqf(sv[tt] * (1.f / 64.f) + GN_EPS) * gw + gb;
;                 const float o = (yn + ((tt & 1) ? bfhi(vbq[tt >> 1]) : bflo(vbq[tt >> 1]))) * ((tt & 1) ? bfhi(ggq[tt >> 1]) : bflo(ggq[tt >> 1]));
;                 YM[(size_t)(row0 + t) * D + gc] = (bf16)f2bf(o); }
;         }
;         LBAR();
;         cur = nxt;
	global_store_short v[34:35], v44, off
	v_mul_f32_e32 v34, v38, v45
	v_fma_f32 v34, v36, v34, v37
	v_and_b32_e32 v28, 0xffff0000, v28
	v_add_f32_e32 v28, v34, v28
	v_and_b32_e32 v24, 0xffff0000, v24
	v_mul_f32_e32 v24, v28, v24
	v_fma_f32 v28, s16, v90, v88
	s_add_i32 s14, s10, -6
	v_rsq_f32_e32 v28, v28
	s_ashr_i32 s15, s14, 31
	s_lshl_b64 s[14:15], s[14:15], 11
	v_cvt_pk_bf16_f32 v24, v24, s0
	v_lshl_add_u64 v[34:35], v[32:33], 0, s[14:15]
	global_store_short v[34:35], v24, off
	v_mul_f32_e32 v24, v39, v28
	v_fma_f32 v24, v36, v24, v37
	v_lshlrev_b32_e32 v28, 16, v29
	v_add_f32_e32 v24, v24, v28
	v_lshlrev_b32_e32 v28, 16, v25
	v_mul_f32_e32 v24, v24, v28
	v_fma_f32 v28, s20, v90, v88
	s_add_i32 s14, s10, -5
	v_rsq_f32_e32 v28, v28
	s_ashr_i32 s15, s14, 31
	s_lshl_b64 s[14:15], s[14:15], 11
	v_cvt_pk_bf16_f32 v24, v24, s0
	v_lshl_add_u64 v[34:35], v[32:33], 0, s[14:15]
	global_store_short v[34:35], v24, off
	v_mul_f32_e32 v24, v41, v28
	v_fma_f32 v24, v36, v24, v37
	v_and_b32_e32 v28, 0xffff0000, v29
	v_add_f32_e32 v24, v24, v28
	v_and_b32_e32 v25, 0xffff0000, v25
	v_mul_f32_e32 v24, v24, v25
	v_cvt_pk_bf16_f32 v28, v24, s0
	v_fma_f32 v24, s17, v90, v88
	s_add_i32 s14, s10, -4
	v_rsq_f32_e32 v29, v24
	s_ashr_i32 s15, s14, 31
	s_lshl_b64 s[14:15], s[14:15], 11
	v_lshl_add_u64 v[24:25], v[32:33], 0, s[14:15]
	global_store_short v[24:25], v28, off
	v_mul_f32_e32 v24, v40, v29
	v_fma_f32 v24, v36, v24, v37
	v_lshlrev_b32_e32 v25, 16, v30
	v_add_f32_e32 v24, v24, v25
	v_lshlrev_b32_e32 v25, 16, v26
	v_mul_f32_e32 v24, v24, v25
	v_cvt_pk_bf16_f32 v28, v24, s0
	v_fma_f32 v24, s21, v90, v88
	s_add_i32 s14, s10, -3
	v_rsq_f32_e32 v29, v24
	s_ashr_i32 s15, s14, 31
	s_lshl_b64 s[14:15], s[14:15], 11
	v_lshl_add_u64 v[24:25], v[32:33], 0, s[14:15]
	global_store_short v[24:25], v28, off
	v_mul_f32_e32 v24, v42, v29
	v_fma_f32 v24, v36, v24, v37
	v_and_b32_e32 v25, 0xffff0000, v30
	v_add_f32_e32 v24, v24, v25
	v_and_b32_e32 v25, 0xffff0000, v26
	v_mul_f32_e32 v24, v24, v25
	v_cvt_pk_bf16_f32 v26, v24, s0
	v_fma_f32 v24, s18, v90, v88
	s_add_i32 s14, s10, -2
	v_rsq_f32_e32 v28, v24
	s_ashr_i32 s15, s14, 31
	s_lshl_b64 s[14:15], s[14:15], 11
	v_lshl_add_u64 v[24:25], v[32:33], 0, s[14:15]
	global_store_short v[24:25], v26, off
	v_mul_f32_e32 v24, v43, v28
	v_fma_f32 v24, v36, v24, v37
	v_lshlrev_b32_e32 v25, 16, v31
	v_add_f32_e32 v24, v24, v25
	v_lshlrev_b32_e32 v25, 16, v27
	v_mul_f32_e32 v24, v24, v25
	v_cvt_pk_bf16_f32 v26, v24, s0
	v_fma_f32 v24, s22, v90, v88
	s_add_i32 s14, s10, -1
	v_rsq_f32_e32 v28, v24
	s_ashr_i32 s15, s14, 31
	s_lshl_b64 s[14:15], s[14:15], 11
	v_lshl_add_u64 v[24:25], v[32:33], 0, s[14:15]
	global_store_short v[24:25], v26, off
	v_mul_f32_e32 v24, v46, v28
	v_fmac_f32_e32 v37, v36, v24
	v_and_b32_e32 v24, 0xffff0000, v31
	v_add_f32_e32 v24, v37, v24
	v_and_b32_e32 v25, 0xffff0000, v27
	s_ashr_i32 s11, s10, 31
	v_mul_f32_e32 v24, v24, v25
	s_lshl_b64 s[10:11], s[10:11], 11
	v_cvt_pk_bf16_f32 v26, v24, s0
	v_lshl_add_u64 v[24:25], v[32:33], 0, s[10:11]
	global_store_short v[24:25], v26, off
	s_waitcnt lgkmcnt(0)
	s_barrier
	s_add_i32 s12, s12, s13
	s_add_i32 s25, s25, s77
	s_add_i32 s24, s24, 1
	s_and_b32 s24, s24, 3
	s_add_i32 s27, s27, 1
	s_min_u32 s27, s27, 3
	s_cmpk_gt_i32 s25, 0x7ff
	s_cbranch_scc1 .LBB0_1679
.Lp7d_top:
	s_add_i32 s28, s25, s77
	s_mov_b32 s26, 0
	s_cmpk_gt_i32 s28, 0x7ff
	s_cbranch_scc1 .Lp7d_f
	s_mov_b32 s26, 1
	s_add_i32 s28, s28, s77
	s_cmpk_gt_i32 s28, 0x7ff
	s_cbranch_scc1 .Lp7d_f
	s_mov_b32 s26, 2
	s_add_i32 s28, s28, s77
.Lp7d_f:
	s_mul_i32 s30, s26, 12
	s_lshl_b32 s31, s27, 3
	s_add_i32 s30, s30, s31
	s_cmp_eq_u32 s30, 48
	s_cbranch_scc1 .Lp7d_w48
	s_cmp_eq_u32 s30, 40
	s_cbranch_scc1 .Lp7d_w40
	s_cmp_eq_u32 s30, 36
	s_cbranch_scc1 .Lp7d_w36
	s_cmp_eq_u32 s30, 32
	s_cbranch_scc1 .Lp7d_w32
	s_cmp_eq_u32 s30, 28
	s_cbranch_scc1 .Lp7d_w28
	s_cmp_eq_u32 s30, 24
	s_cbranch_scc1 .Lp7d_w24
	s_cmp_eq_u32 s30, 20
	s_cbranch_scc1 .Lp7d_w20
	s_cmp_eq_u32 s30, 16
	s_cbranch_scc1 .Lp7d_w16
	s_cmp_eq_u32 s30, 12
	s_cbranch_scc1 .Lp7d_w12
	s_cmp_eq_u32 s30, 8
	s_cbranch_scc1 .Lp7d_w8
	s_cmp_eq_u32 s30, 0
	s_cbranch_scc1 .Lp7d_w0
	s_waitcnt vmcnt(0)
	s_branch .Lp7d_wd
.Lp7d_w48:
	s_waitcnt vmcnt(48)
	s_branch .Lp7d_wd
.Lp7d_w40:
	s_waitcnt vmcnt(40)
	s_branch .Lp7d_wd
.Lp7d_w36:
	s_waitcnt vmcnt(36)
	s_branch .Lp7d_wd
.Lp7d_w32:
	s_waitcnt vmcnt(32)
	s_branch .Lp7d_wd
.Lp7d_w28:
	s_waitcnt vmcnt(28)
	s_branch .Lp7d_wd
.Lp7d_w24:
	s_waitcnt vmcnt(24)
	s_branch .Lp7d_wd
.Lp7d_w20:
	s_waitcnt vmcnt(20)
	s_branch .Lp7d_wd
.Lp7d_w16:
	s_waitcnt vmcnt(16)
	s_branch .Lp7d_wd
.Lp7d_w12:
	s_waitcnt vmcnt(12)
	s_branch .Lp7d_wd
.Lp7d_w8:
	s_waitcnt vmcnt(8)
	s_branch .Lp7d_wd
.Lp7d_w0:
	s_waitcnt vmcnt(0)
	s_branch .Lp7d_wd
.Lp7d_wd:
	s_cmp_lg_u32 s26, 2
	s_cbranch_scc1 .Lp7d_copy
	s_cmpk_gt_i32 s28, 0x7ff
	s_cbranch_scc1 .Lp7d_copy
	s_cmp_eq_u32 s24, 0
	s_cbranch_scc1 .Lp7d_ld0
	s_cmp_eq_u32 s24, 1
	s_cbranch_scc1 .Lp7d_ld1
	s_cmp_eq_u32 s24, 2
	s_cbranch_scc1 .Lp7d_ld2
	s_cmp_eq_u32 s24, 3
	s_cbranch_scc1 .Lp7d_ld3
.Lp7d_ld0:
	s_ashr_i32 s29, s28, 31
	s_lshl_b64 s[30:31], s[28:29], 13
	v_lshl_add_u64 v[2:3], v[62:63], 0, s[30:31]
	v_lshl_add_u64 v[4:5], v[2:3], 0, v[56:57]
	global_load_dwordx4 v[218:221], v[4:5], off
	global_load_dwordx4 v[222:225], v[4:5], off offset:64
	v_lshl_add_u64 v[4:5], v[64:65], 0, s[30:31]
	global_load_dwordx4 v[226:229], v[4:5], off
	global_load_dwordx4 v[230:233], v[4:5], off offset:64
	v_lshl_add_u64 v[4:5], v[66:67], 0, s[30:31]
	global_load_dwordx2 v[242:243], v[4:5], off
	global_load_dwordx2 v[244:245], v[4:5], off offset:32
	v_lshl_add_u64 v[4:5], v[2:3], 0, v[68:69]
	global_load_dwordx4 v[234:237], v[4:5], off
	global_load_dwordx4 v[238:241], v[4:5], off offset:64
	v_lshl_add_u64 v[4:5], v[58:59], 0, s[30:31]
	global_load_dwordx4 v[246:249], v[4:5], off
	v_lshl_add_u64 v[4:5], v[60:61], 0, s[30:31]
	global_load_dwordx4 v[250:253], v[4:5], off
	s_lshr_b32 s99, s28, 6
	s_and_b32 s99, s99, 7
	s_lshl_b32 s99, s99, 6
	v_add_lshl_u32 v6, v208, s99, 2
	v_mov_b32_e32 v7, 0
	v_lshl_add_u64 v[4:5], s[0:1], 0, v[6:7]
	global_load_dword v0, v[4:5], off
	v_lshl_add_u64 v[4:5], s[2:3], 0, v[6:7]
	global_load_dword v1, v[4:5], off
	s_branch .Lp7d_copy
; #define GAS __attribute__((address_space(1)))
; __device__ __forceinline__ void chunk_out_load(Frame& F, int item, ChunkOutOps& o, int w, int fr, int fq) {
;     const bf16* S = (const bf16*)(F.ws + WS_S) + (size_t)item * 4096; const bf16* RP = (const bf16*)(F.ws + WS_RP) + (size_t)item * 4096; const bf16* Y0 = (const bf16*)(F.ws + WS_Y0) + (size_t)item * 4096;
; #pragma unroll
;     for (int q = 0; q < 2; ++q) { const int tw = 2 * w + q, p0 = 16 * (tw >> 2), q0 = 16 * (tw & 3);
;         o.y0[q] = *(const GAS v2u*)(Y0 + (p0 + fr) * 64 + q0 + 4 * fq);
; #pragma unroll
;         for (int k = 0; k < 2; ++k) { o.sf[q][k] = *(const GAS bf16x8*)(S + (q0 + fr) * 64 + k * 32 + fq * 8); o.rf[q][k] = *(const GAS bf16x8*)(RP + (p0 + fr) * 64 + k * 32 + fq * 8); } }
; }
; __device__ __forceinline__ void rwkv_chunk_out_all(Frame& F) {
;     ...
;         const v4u vbq = *(const GAS v4u*)(VB + ch * 64 + 8 * w), ggq = *(const GAS v4u*)(G + ch * 64 + 8 * w);
;         const int inext = item + F.G;
;         if (inext < NITEM) chunk_out_load(F, inext, nxt, w, fr, fq);
.Lp7d_ld1:
	s_ashr_i32 s29, s28, 31
	s_lshl_b64 s[30:31], s[28:29], 13
	v_lshl_add_u64 v[2:3], v[62:63], 0, s[30:31]
	v_lshl_add_u64 v[4:5], v[2:3], 0, v[56:57]
	global_load_dwordx4 v[102:105], v[4:5], off
	global_load_dwordx4 v[106:109], v[4:5], off offset:64
	v_lshl_add_u64 v[4:5], v[64:65], 0, s[30:31]
	global_load_dwordx4 v[110:113], v[4:5], off
	global_load_dwordx4 v[114:117], v[4:5], off offset:64
	v_lshl_add_u64 v[4:5], v[66:67], 0, s[30:31]
	global_load_dwordx2 v[126:127], v[4:5], off
	global_load_dwordx2 v[128:129], v[4:5], off offset:32
	v_lshl_add_u64 v[4:5], v[2:3], 0, v[68:69]
	global_load_dwordx4 v[118:121], v[4:5], off
	global_load_dwordx4 v[122:125], v[4:5], off offset:64
	v_lshl_add_u64 v[4:5], v[58:59], 0, s[30:31]
	global_load_dwordx4 v[130:133], v[4:5], off
	v_lshl_add_u64 v[4:5], v[60:61], 0, s[30:31]
	global_load_dwordx4 v[134:137], v[4:5], off
	s_lshr_b32 s99, s28, 6
	s_and_b32 s99, s99, 7
	s_lshl_b32 s99, s99, 6
	v_add_lshl_u32 v6, v208, s99, 2
	v_mov_b32_e32 v7, 0
	v_lshl_add_u64 v[4:5], s[0:1], 0, v[6:7]
	global_load_dword v138, v[4:5], off
	v_lshl_add_u64 v[4:5], s[2:3], 0, v[6:7]
	global_load_dword v139, v[4:5], off
	s_branch .Lp7d_copy
.Lp7d_ld2:
	s_ashr_i32 s29, s28, 31
	s_lshl_b64 s[30:31], s[28:29], 13
	v_lshl_add_u64 v[2:3], v[62:63], 0, s[30:31]
	v_lshl_add_u64 v[4:5], v[2:3], 0, v[56:57]
	global_load_dwordx4 v[140:143], v[4:5], off
	global_load_dwordx4 v[144:147], v[4:5], off offset:64
	v_lshl_add_u64 v[4:5], v[64:65], 0, s[30:31]
	global_load_dwordx4 v[148:151], v[4:5], off
	global_load_dwordx4 v[152:155], v[4:5], off offset:64
	v_lshl_add_u64 v[4:5], v[66:67], 0, s[30:31]
	global_load_dwordx2 v[164:165], v[4:5], off
	global_load_dwordx2 v[166:167], v[4:5], off offset:32
	v_lshl_add_u64 v[4:5], v[2:3], 0, v[68:69]
	global_load_dwordx4 v[156:159], v[4:5], off
	global_load_dwordx4 v[160:163], v[4:5], off offset:64
	v_lshl_add_u64 v[4:5], v[58:59], 0, s[30:31]
	global_load_dwordx4 v[168:171], v[4:5], off
	v_lshl_add_u64 v[4:5], v[60:61], 0, s[30:31]
	global_load_dwordx4 v[172:175], v[4:5], off
	s_lshr_b32 s99, s28, 6
	s_and_b32 s99, s99, 7
	s_lshl_b32 s99, s99, 6
	v_add_lshl_u32 v6, v208, s99, 2
	v_mov_b32_e32 v7, 0
	v_lshl_add_u64 v[4:5], s[0:1], 0, v[6:7]
	global_load_dword v176, v[4:5], off
	v_lshl_add_u64 v[4:5], s[2:3], 0, v[6:7]
	global_load_dword v177, v[4:5], off
	s_branch .Lp7d_copy
.Lp7d_ld3:
	s_ashr_i32 s29, s28, 31
	s_lshl_b64 s[30:31], s[28:29], 13
	v_lshl_add_u64 v[2:3], v[62:63], 0, s[30:31]
	v_lshl_add_u64 v[4:5], v[2:3], 0, v[56:57]
	global_load_dwordx4 v[178:181], v[4:5], off
	global_load_dwordx4 v[182:185], v[4:5], off offset:64
	v_lshl_add_u64 v[4:5], v[64:65], 0, s[30:31]
	global_load_dwordx4 v[186:189], v[4:5], off
	global_load_dwordx4 v[190:193], v[4:5], off offset:64
	v_lshl_add_u64 v[4:5], v[66:67], 0, s[30:31]
	global_load_dwordx2 v[202:203], v[4:5], off
	global_load_dwordx2 v[204:205], v[4:5], off offset:32
	v_lshl_add_u64 v[4:5], v[2:3], 0, v[68:69]
	global_load_dwordx4 v[194:197], v[4:5], off
	global_load_dwordx4 v[198:201], v[4:5], off offset:64
	v_lshl_add_u64 v[4:5], v[58:59], 0, s[30:31]
	global_load_dwordx4 v[210:213], v[4:5], off
	v_lshl_add_u64 v[4:5], v[60:61], 0, s[30:31]
	global_load_dwordx4 v[214:217], v[4:5], off
	s_lshr_b32 s99, s28, 6
	s_and_b32 s99, s99, 7
	s_lshl_b32 s99, s99, 6
	v_add_lshl_u32 v6, v208, s99, 2
	v_mov_b32_e32 v7, 0
	v_lshl_add_u64 v[4:5], s[0:1], 0, v[6:7]
	global_load_dword v206, v[4:5], off
	v_lshl_add_u64 v[4:5], s[2:3], 0, v[6:7]
	global_load_dword v207, v[4:5], off
	s_branch .Lp7d_copy
.Lp7d_copy:
	s_cmp_eq_u32 s24, 0
	s_cbranch_scc1 .Lp7d_cp0
	s_cmp_eq_u32 s24, 1
	s_cbranch_scc1 .Lp7d_cp1
	s_cmp_eq_u32 s24, 2
	s_cbranch_scc1 .Lp7d_cp2
	s_cmp_eq_u32 s24, 3
	s_cbranch_scc1 .Lp7d_cp3
; #define GAS __attribute__((address_space(1)))
; __device__ __forceinline__ void rwkv_chunk_out_all(Frame& F) {
;     ...
;     for (; item < NITEM; item += F.G) {
;         const int bh = item / NCH, c = item % NCH, b = bh / RW_H, h = bh % RW_H; const int row0 = b * T + c * CH;
;         const int ch = lane, gc = h * 64 + ch;
;         const bf16* VB = (const bf16*)(F.ws + WS_VB) + (size_t)item * 4096; const bf16* G = (const bf16*)(F.ws + WS_G) + (size_t)item * 4096;
;         const v4u vbq = *(const GAS v4u*)(VB + ch * 64 + 8 * w), ggq = *(const GAS v4u*)(G + ch * 64 + 8 * w);
;         const int inext = item + F.G;
;         if (inext < NITEM) chunk_out_load(F, inext, nxt, w, fr, fq);
;     ...
;         cur = nxt;
.Lp7d_cp0:
	v_mov_b32_e32 v52, v102
	v_mov_b32_e32 v53, v103
	v_mov_b32_e32 v54, v104
	v_mov_b32_e32 v55, v105
	v_mov_b32_e32 v48, v106
	v_mov_b32_e32 v49, v107
	v_mov_b32_e32 v50, v108
	v_mov_b32_e32 v51, v109
	v_mov_b32_e32 v36, v110
	v_mov_b32_e32 v37, v111
	v_mov_b32_e32 v38, v112
	v_mov_b32_e32 v39, v113
	v_mov_b32_e32 v32, v114
	v_mov_b32_e32 v33, v115
	v_mov_b32_e32 v34, v116
	v_mov_b32_e32 v35, v117
	v_mov_b32_e32 v44, v118
	v_mov_b32_e32 v45, v119
	v_mov_b32_e32 v46, v120
	v_mov_b32_e32 v47, v121
	v_mov_b32_e32 v40, v122
	v_mov_b32_e32 v41, v123
	v_mov_b32_e32 v42, v124
	v_mov_b32_e32 v43, v125
	v_mov_b32_e32 v76, v126
	v_mov_b32_e32 v77, v127
	v_mov_b32_e32 v74, v128
	v_mov_b32_e32 v75, v129
	v_mov_b32_e32 v28, v130
	v_mov_b32_e32 v29, v131
	v_mov_b32_e32 v30, v132
	v_mov_b32_e32 v31, v133
	v_mov_b32_e32 v24, v134
	v_mov_b32_e32 v25, v135
	v_mov_b32_e32 v26, v136
	v_mov_b32_e32 v27, v137
	v_mov_b32_e32 v100, v138
	v_mov_b32_e32 v101, v139
	s_branch .Lp7d_go
.Lp7d_cp1:
	v_mov_b32_e32 v52, v140
	v_mov_b32_e32 v53, v141
	v_mov_b32_e32 v54, v142
	v_mov_b32_e32 v55, v143
	v_mov_b32_e32 v48, v144
	v_mov_b32_e32 v49, v145
	v_mov_b32_e32 v50, v146
	v_mov_b32_e32 v51, v147
	v_mov_b32_e32 v36, v148
	v_mov_b32_e32 v37, v149
	v_mov_b32_e32 v38, v150
	v_mov_b32_e32 v39, v151
	v_mov_b32_e32 v32, v152
	v_mov_b32_e32 v33, v153
	v_mov_b32_e32 v34, v154
	v_mov_b32_e32 v35, v155
	v_mov_b32_e32 v44, v156
	v_mov_b32_e32 v45, v157
	v_mov_b32_e32 v46, v158
	v_mov_b32_e32 v47, v159
	v_mov_b32_e32 v40, v160
	v_mov_b32_e32 v41, v161
	v_mov_b32_e32 v42, v162
	v_mov_b32_e32 v43, v163
	v_mov_b32_e32 v76, v164
	v_mov_b32_e32 v77, v165
	v_mov_b32_e32 v74, v166
	v_mov_b32_e32 v75, v167
	v_mov_b32_e32 v28, v168
	v_mov_b32_e32 v29, v169
	v_mov_b32_e32 v30, v170
	v_mov_b32_e32 v31, v171
	v_mov_b32_e32 v24, v172
	v_mov_b32_e32 v25, v173
	v_mov_b32_e32 v26, v174
	v_mov_b32_e32 v27, v175
	v_mov_b32_e32 v100, v176
	v_mov_b32_e32 v101, v177
	s_branch .Lp7d_go
.Lp7d_cp2:
	v_mov_b32_e32 v52, v178
	v_mov_b32_e32 v53, v179
	v_mov_b32_e32 v54, v180
	v_mov_b32_e32 v55, v181
	v_mov_b32_e32 v48, v182
	v_mov_b32_e32 v49, v183
	v_mov_b32_e32 v50, v184
	v_mov_b32_e32 v51, v185
	v_mov_b32_e32 v36, v186
	v_mov_b32_e32 v37, v187
	v_mov_b32_e32 v38, v188
	v_mov_b32_e32 v39, v189
	v_mov_b32_e32 v32, v190
	v_mov_b32_e32 v33, v191
	v_mov_b32_e32 v34, v192
	v_mov_b32_e32 v35, v193
	v_mov_b32_e32 v44, v194
	v_mov_b32_e32 v45, v195
	v_mov_b32_e32 v46, v196
	v_mov_b32_e32 v47, v197
	v_mov_b32_e32 v40, v198
	v_mov_b32_e32 v41, v199
	v_mov_b32_e32 v42, v200
	v_mov_b32_e32 v43, v201
	v_mov_b32_e32 v76, v202
	v_mov_b32_e32 v77, v203
	v_mov_b32_e32 v74, v204
	v_mov_b32_e32 v75, v205
	v_mov_b32_e32 v28, v210
	v_mov_b32_e32 v29, v211
	v_mov_b32_e32 v30, v212
	v_mov_b32_e32 v31, v213
	v_mov_b32_e32 v24, v214
	v_mov_b32_e32 v25, v215
	v_mov_b32_e32 v26, v216
	v_mov_b32_e32 v27, v217
	v_mov_b32_e32 v100, v206
	v_mov_b32_e32 v101, v207
	s_branch .Lp7d_go
.Lp7d_cp3:
	v_mov_b32_e32 v52, v218
	v_mov_b32_e32 v53, v219
	v_mov_b32_e32 v54, v220
	v_mov_b32_e32 v55, v221
	v_mov_b32_e32 v48, v222
	v_mov_b32_e32 v49, v223
	v_mov_b32_e32 v50, v224
	v_mov_b32_e32 v51, v225
	v_mov_b32_e32 v36, v226
	v_mov_b32_e32 v37, v227
	v_mov_b32_e32 v38, v228
	v_mov_b32_e32 v39, v229
	v_mov_b32_e32 v32, v230
	v_mov_b32_e32 v33, v231
	v_mov_b32_e32 v34, v232
	v_mov_b32_e32 v35, v233
	v_mov_b32_e32 v44, v234
	v_mov_b32_e32 v45, v235
	v_mov_b32_e32 v46, v236
	v_mov_b32_e32 v47, v237
	v_mov_b32_e32 v40, v238
	v_mov_b32_e32 v41, v239
	v_mov_b32_e32 v42, v240
	v_mov_b32_e32 v43, v241
	v_mov_b32_e32 v76, v242
	v_mov_b32_e32 v77, v243
	v_mov_b32_e32 v74, v244
	v_mov_b32_e32 v75, v245
	v_mov_b32_e32 v28, v246
	v_mov_b32_e32 v29, v247
	v_mov_b32_e32 v30, v248
	v_mov_b32_e32 v31, v249
	v_mov_b32_e32 v24, v250
	v_mov_b32_e32 v25, v251
	v_mov_b32_e32 v26, v252
	v_mov_b32_e32 v27, v253
	v_mov_b32_e32 v100, v0
	v_mov_b32_e32 v101, v1
	s_branch .Lp7d_go
.Lp7d_go:
	s_mov_b32 s10, s25
	s_ashr_i32 s11, s10, 31
	s_branch .Lp7_body


